# second aliasing guard: down-GEMM completions counted (word 122) and awaited at the proj->mixer seam before any mixer phase writes Yg/ycat/PV (which alias other batches' act rows)
# speedup vs baseline: 1.0075x; 1.0003x over previous
; #define LAS __attribute__((address_space(3)))
; #define GRID_SYNC() do { XcdBarrier b_; b_.bar = (unsigned*)(args.ws + WS_BAR); b_.x = xb_xcc_id(); b_.st = (volatile LAS unsigned*)(lds + 147440); xcd_barrier(b_); } while (0)
; __global__ void __launch_bounds__(512, 2) fwd_megakernel(Args args) {
;     ...
;             {
;                 pg8::Gemm g{actb, Wl + (half ? WL_D2 : WL_D1) / 2, MTOK, DM, DFF}; pg8::StaticOrder S; S.init(MTOK, DM, G, bid);
;                 EpiResid E{xb, ssq + (size_t)(3 * layer + 2 * half + 1) * MTOK * 4, 0.5f, (LAS float*)(lds + 131072)};
;                 pg8::gemm_phase<EpiResid, pg8::StaticOrder, true, true>(lds, g, S, E);
;             }
;             GRID_SYNC();
.LBB0_267:
	s_getreg_b32 s2, hwreg(HW_REG_XCC_ID, 0, 4)
	s_waitcnt vmcnt(0)
	s_waitcnt lgkmcnt(0)
	s_barrier
	s_and_saveexec_b64 s[4:5], s[76:77]
	s_cbranch_execz .LBB0_319
	s_add_u32 s8, s80, 0x101e8
	s_addc_u32 s9, s81, 0
	v_mov_b32_e32 v0, 0
	v_mov_b32_e32 v1, 1
	global_atomic_add v0, v1, s[8:9]
	v_mov_b32_e32 v0, 0x23ff8
	ds_read_b32 v2, v0
	s_waitcnt lgkmcnt(0)
	v_readfirstlane_b32 s3, v2
	s_cmp_eq_u32 s3, 1
	s_cbranch_scc1 .Lfb3_fast
	s_branch .Lfb3_slow

; #define GRID_SYNC() do { XcdBarrier b_; b_.bar = (unsigned*)(args.ws + WS_BAR); b_.x = xb_xcc_id(); b_.st = (volatile LAS unsigned*)(lds + 147440); xcd_barrier(b_); } while (0)
; __global__ void __launch_bounds__(512, 2) fwd_megakernel(Args args) {
;     ...
;             GRID_SYNC();
.Lfb4_rel:
	v_readlane_b32 s3, v253, 58
	s_lshl_b32 s3, s3, 6
	s_add_u32 s7, s3, 0x100
	s_add_u32 s8, s80, 0x101e8
	s_addc_u32 s9, s81, 0
	v_mov_b32_e32 v0, 0
	s_mov_b32 s16, 0
.Lfb4_vspin:
	global_load_dword v2, v0, s[8:9] sc1
	s_waitcnt vmcnt(0)
	v_readfirstlane_b32 s3, v2
	s_cmp_ge_u32 s3, s7
	s_cbranch_scc1 .Lfb4_vok
	s_sleep 1
	s_add_i32 s16, s16, 1
	s_cmp_lt_u32 s16, 0x8000
	s_cbranch_scc1 .Lfb4_vspin
